# adds straight-line 4-deep LDS-prefetched accd MFMA chain (wave-uniform exits) replacing the exec-masked read-wait-MFMA loop
# speedup vs baseline: 1.0152x; 1.0057x over previous
; #define LAS __attribute__((address_space(3)))
; __device__ __forceinline__ f32x16 mma32_k(const LAS bf16_t* A, const LAS bf16_t* B, int ksteps, f32x16 acc, int lane) {
;     const LAS bf16_t* ap = A + (lane & 31) * SLD + (lane >> 5) * 8; const LAS bf16_t* bp = B + (lane & 31) * SLD + (lane >> 5) * 8;
;     for (int ks = 0; ks < ksteps; ks += 2) {
;         const bf16x8 a0 = *(const LAS bf16x8*)(ap + ks * 16), a1 = *(const LAS bf16x8*)(ap + ks * 16 + 16);
;         const bf16x8 b0 = *(const LAS bf16x8*)(bp + ks * 16), b1 = *(const LAS bf16x8*)(bp + ks * 16 + 16);
;         acc = __builtin_amdgcn_mfma_f32_32x32x16_bf16(a0, b0, acc, 0, 0, 0);
;         acc = __builtin_amdgcn_mfma_f32_32x32x16_bf16(a1, b1, acc, 0, 0, 0); }
;     return acc;
; __device__ __forceinline__ void ssd_item(const Params& p, LAS unsigned char* lds, int bl, int head, int dry) {
;     ...
;           accd = mma32_k(XT + pc * 32 * SLD, BMm + i * 32 * SLD, 2 * (i + 1), accd, lane);
.LBB0_324:
	s_or_b64 exec, exec, s[56:57]
	v_mov_b32_e32 v31, 0
	v_mov_b32_e32 v30, v31
	v_mov_b32_e32 v29, v31
	v_mov_b32_e32 v28, v31
	v_mov_b32_e32 v27, v31
	v_mov_b32_e32 v26, v31
	v_mov_b32_e32 v25, v31
	v_mov_b32_e32 v24, v31
	v_mov_b32_e32 v23, v31
	v_mov_b32_e32 v22, v31
	v_mov_b32_e32 v21, v31
	v_mov_b32_e32 v20, v31
	v_mov_b32_e32 v19, v31
	v_mov_b32_e32 v18, v31
	v_mov_b32_e32 v17, v31
	v_mov_b32_e32 v16, v31
	s_waitcnt lgkmcnt(0)
	s_barrier
	s_and_saveexec_b64 s[0:1], s[44:45]
	s_cbranch_execz .LBB0_223
	v_readfirstlane_b32 s2, v172
	v_subrev_u32_e32 v32, 32, v184
	ds_read_b128 v[34:37], v32
	ds_read_b128 v[38:41], v183
	ds_read_b128 v[194:197], v32 offset:32
	ds_read_b128 v[206:209], v183 offset:32
	s_cmp_lt_u32 s2, 2
	s_cbranch_scc1 .Lad_n2
	ds_read_b128 v[198:201], v32 offset:64
	ds_read_b128 v[210:213], v183 offset:64
	ds_read_b128 v[202:205], v32 offset:96
	ds_read_b128 v[214:217], v183 offset:96
	s_cmp_lt_u32 s2, 4
	s_cbranch_scc1 .Lad_n4
	s_waitcnt lgkmcnt(6)
	v_mfma_f32_32x32x16_bf16 v[16:31], v[34:37], v[38:41], 0
	ds_read_b128 v[34:37], v32 offset:128
	ds_read_b128 v[38:41], v183 offset:128
	s_waitcnt lgkmcnt(6)
	v_mfma_f32_32x32x16_bf16 v[16:31], v[194:197], v[206:209], v[16:31]
	ds_read_b128 v[194:197], v32 offset:160
	ds_read_b128 v[206:209], v183 offset:160
	s_cmp_lt_u32 s2, 6
	s_cbranch_scc1 .Lad_n6
	s_waitcnt lgkmcnt(6)
	v_mfma_f32_32x32x16_bf16 v[16:31], v[198:201], v[210:213], v[16:31]
	ds_read_b128 v[198:201], v32 offset:192
	ds_read_b128 v[210:213], v183 offset:192
	s_waitcnt lgkmcnt(6)
	v_mfma_f32_32x32x16_bf16 v[16:31], v[202:205], v[214:217], v[16:31]
	ds_read_b128 v[202:205], v32 offset:224
	ds_read_b128 v[214:217], v183 offset:224
	s_waitcnt lgkmcnt(6)
	v_mfma_f32_32x32x16_bf16 v[16:31], v[34:37], v[38:41], v[16:31]
	s_waitcnt lgkmcnt(4)
	v_mfma_f32_32x32x16_bf16 v[16:31], v[194:197], v[206:209], v[16:31]
	s_waitcnt lgkmcnt(2)
	v_mfma_f32_32x32x16_bf16 v[16:31], v[198:201], v[210:213], v[16:31]
	s_waitcnt lgkmcnt(0)
	v_mfma_f32_32x32x16_bf16 v[16:31], v[202:205], v[214:217], v[16:31]
	s_branch .LBB0_223
.Lad_n6:
	s_waitcnt lgkmcnt(6)
	v_mfma_f32_32x32x16_bf16 v[16:31], v[198:201], v[210:213], v[16:31]
	s_waitcnt lgkmcnt(4)
	v_mfma_f32_32x32x16_bf16 v[16:31], v[202:205], v[214:217], v[16:31]
	s_waitcnt lgkmcnt(2)
	v_mfma_f32_32x32x16_bf16 v[16:31], v[34:37], v[38:41], v[16:31]
	s_waitcnt lgkmcnt(0)
	v_mfma_f32_32x32x16_bf16 v[16:31], v[194:197], v[206:209], v[16:31]
	s_branch .LBB0_223
.Lad_n4:
	s_waitcnt lgkmcnt(6)
	v_mfma_f32_32x32x16_bf16 v[16:31], v[34:37], v[38:41], 0
	s_waitcnt lgkmcnt(4)
	v_mfma_f32_32x32x16_bf16 v[16:31], v[194:197], v[206:209], v[16:31]
	s_waitcnt lgkmcnt(2)
	v_mfma_f32_32x32x16_bf16 v[16:31], v[198:201], v[210:213], v[16:31]
	s_waitcnt lgkmcnt(0)
	v_mfma_f32_32x32x16_bf16 v[16:31], v[202:205], v[214:217], v[16:31]
	s_branch .LBB0_223
.Lad_n2:
	s_waitcnt lgkmcnt(2)
	v_mfma_f32_32x32x16_bf16 v[16:31], v[34:37], v[38:41], 0
	s_waitcnt lgkmcnt(0)
	v_mfma_f32_32x32x16_bf16 v[16:31], v[194:197], v[206:209], v[16:31]
	s_branch .LBB0_223
